# P6 epilogue hand-written (permlane16_swap), P6/P7 tile-header vmcnt(0) drains removed (token offsets converted at tile switch)
# speedup vs baseline: 1.0758x; 1.0056x over previous
.LBB0_1357:
	s_nop 7
	s_nop 7
	s_mul_hi_u32 s0, s37, 0xaaaaaaab
	s_lshr_b32 s0, s0, 6
	v_readlane_b32 s10, v245, 12
	s_add_i32 s10, s0, s10
	s_mulk_i32 s0, 0x60
	s_sub_i32 s0, s37, s0
	s_mul_i32 s11, s0, 0xab
	s_bfe_u32 s11, s11, 0x6000a
	s_mul_i32 s38, s11, 6
	s_sub_i32 s0, s0, s38
	s_and_b32 s0, s0, 0xff
	s_lshl_b32 s0, s0, 19
	s_mul_hi_u32 s37, s10, 0x300000
	s_mul_i32 s10, s10, 0x300000
	s_add_u32 s0, s24, s0
	s_addc_u32 s38, s25, 0
	s_add_u32 s0, s0, s10
	s_addc_u32 s37, s38, s37
	s_lshl_b32 s10, s11, 7
	s_add_u32 s10, s0, s10
	s_addc_u32 s11, s37, 0
	v_lshl_add_u32 v204, v197, 2, v218
	v_lshlrev_b32_e32 v204, 11, v204
	v_add3_u32 v204, v204, v198, v200
	v_add_u32_e32 v205, 0x1000, v204
	v_permlane16_swap_b32_e32 v114, v82
	v_permlane16_swap_b32_e32 v98, v66
	v_permlane16_swap_b32_e32 v115, v83
	v_permlane16_swap_b32_e32 v99, v67
	v_permlane16_swap_b32_e32 v116, v84
	v_permlane16_swap_b32_e32 v100, v68
	v_permlane16_swap_b32_e32 v117, v85
	v_permlane16_swap_b32_e32 v101, v69
	v_mul_f32_e32 v181, 0xbfb8aa3b, v114
	v_mul_f32_e32 v193, 0xbfb8aa3b, v98
	v_mul_f32_e32 v195, 0xbfb8aa3b, v115
	v_mul_f32_e32 v199, 0xbfb8aa3b, v99
	v_mul_f32_e32 v201, 0xbfb8aa3b, v116
	v_mul_f32_e32 v202, 0xbfb8aa3b, v100
	v_mul_f32_e32 v203, 0xbfb8aa3b, v117
	v_mul_f32_e32 v206, 0xbfb8aa3b, v101
	v_exp_f32_e32 v181, v181
	v_exp_f32_e32 v193, v193
	v_exp_f32_e32 v195, v195
	v_exp_f32_e32 v199, v199
	v_exp_f32_e32 v201, v201
	v_exp_f32_e32 v202, v202
	v_exp_f32_e32 v203, v203
	v_exp_f32_e32 v206, v206
	v_add_f32_e32 v181, 1.0, v181
	v_add_f32_e32 v193, 1.0, v193
	v_add_f32_e32 v195, 1.0, v195
	v_add_f32_e32 v199, 1.0, v199
	v_add_f32_e32 v201, 1.0, v201
	v_add_f32_e32 v202, 1.0, v202
	v_add_f32_e32 v203, 1.0, v203
	v_add_f32_e32 v206, 1.0, v206
	v_rcp_f32_e32 v181, v181
	v_rcp_f32_e32 v193, v193
	v_rcp_f32_e32 v195, v195
	v_rcp_f32_e32 v199, v199
	v_rcp_f32_e32 v201, v201
	v_rcp_f32_e32 v202, v202
	v_rcp_f32_e32 v203, v203
	v_rcp_f32_e32 v206, v206
	v_mul_f32_e32 v114, v114, v181
	v_mul_f32_e32 v98, v98, v193
	v_mul_f32_e32 v115, v115, v195
	v_mul_f32_e32 v99, v99, v199
	v_mul_f32_e32 v116, v116, v201
	v_mul_f32_e32 v100, v100, v202
	v_mul_f32_e32 v117, v117, v203
	v_mul_f32_e32 v101, v101, v206
	v_mul_f32_e32 v82, v82, v114
	v_mul_f32_e32 v66, v66, v98
	v_mul_f32_e32 v83, v83, v115
	v_mul_f32_e32 v67, v67, v99
	v_mul_f32_e32 v84, v84, v116
	v_mul_f32_e32 v68, v68, v100
	v_mul_f32_e32 v85, v85, v117
	v_mul_f32_e32 v69, v69, v101
	v_cvt_pk_bf16_f32 v114, v82, v66
	v_cvt_pk_bf16_f32 v115, v83, v67
	v_cvt_pk_bf16_f32 v116, v84, v68
	v_cvt_pk_bf16_f32 v117, v85, v69
	global_store_dword v204, v114, s[10:11]
	global_store_dword v204, v115, s[10:11] offset:2048
	global_store_dword v205, v116, s[10:11]
	global_store_dword v205, v117, s[10:11] offset:2048
	s_add_u32 s10, s10, 0x4000
	s_addc_u32 s11, s11, 0
	v_permlane16_swap_b32_e32 v118, v86
	v_permlane16_swap_b32_e32 v102, v70
	v_permlane16_swap_b32_e32 v119, v87
	v_permlane16_swap_b32_e32 v103, v71
	v_permlane16_swap_b32_e32 v120, v88
	v_permlane16_swap_b32_e32 v104, v72
	v_permlane16_swap_b32_e32 v121, v89
	v_permlane16_swap_b32_e32 v105, v73
	v_mul_f32_e32 v181, 0xbfb8aa3b, v118
	v_mul_f32_e32 v193, 0xbfb8aa3b, v102
	v_mul_f32_e32 v195, 0xbfb8aa3b, v119
	v_mul_f32_e32 v199, 0xbfb8aa3b, v103
	v_mul_f32_e32 v201, 0xbfb8aa3b, v120
	v_mul_f32_e32 v202, 0xbfb8aa3b, v104
	v_mul_f32_e32 v203, 0xbfb8aa3b, v121
	v_mul_f32_e32 v206, 0xbfb8aa3b, v105
	v_exp_f32_e32 v181, v181
	v_exp_f32_e32 v193, v193
	v_exp_f32_e32 v195, v195
	v_exp_f32_e32 v199, v199
	v_exp_f32_e32 v201, v201
	v_exp_f32_e32 v202, v202
	v_exp_f32_e32 v203, v203
	v_exp_f32_e32 v206, v206
	v_add_f32_e32 v181, 1.0, v181
	v_add_f32_e32 v193, 1.0, v193
	v_add_f32_e32 v195, 1.0, v195
	v_add_f32_e32 v199, 1.0, v199
	v_add_f32_e32 v201, 1.0, v201
	v_add_f32_e32 v202, 1.0, v202
	v_add_f32_e32 v203, 1.0, v203
	v_add_f32_e32 v206, 1.0, v206
	v_rcp_f32_e32 v181, v181
	v_rcp_f32_e32 v193, v193
	v_rcp_f32_e32 v195, v195
	v_rcp_f32_e32 v199, v199
	v_rcp_f32_e32 v201, v201
	v_rcp_f32_e32 v202, v202
	v_rcp_f32_e32 v203, v203
	v_rcp_f32_e32 v206, v206
	v_mul_f32_e32 v118, v118, v181
	v_mul_f32_e32 v102, v102, v193
	v_mul_f32_e32 v119, v119, v195
	v_mul_f32_e32 v103, v103, v199
	v_mul_f32_e32 v120, v120, v201
	v_mul_f32_e32 v104, v104, v202
	v_mul_f32_e32 v121, v121, v203
	v_mul_f32_e32 v105, v105, v206
	v_mul_f32_e32 v86, v86, v118
	v_mul_f32_e32 v70, v70, v102
	v_mul_f32_e32 v87, v87, v119
	v_mul_f32_e32 v71, v71, v103
	v_mul_f32_e32 v88, v88, v120
	v_mul_f32_e32 v72, v72, v104
	v_mul_f32_e32 v89, v89, v121
	v_mul_f32_e32 v73, v73, v105
	v_cvt_pk_bf16_f32 v118, v86, v70
	v_cvt_pk_bf16_f32 v119, v87, v71
	v_cvt_pk_bf16_f32 v120, v88, v72
	v_cvt_pk_bf16_f32 v121, v89, v73
	global_store_dword v204, v118, s[10:11]
	global_store_dword v204, v119, s[10:11] offset:2048
	global_store_dword v205, v120, s[10:11]
	global_store_dword v205, v121, s[10:11] offset:2048
	s_add_u32 s10, s10, 0x4000
	s_addc_u32 s11, s11, 0
	v_permlane16_swap_b32_e32 v122, v90
	v_permlane16_swap_b32_e32 v106, v74
	v_permlane16_swap_b32_e32 v123, v91
	v_permlane16_swap_b32_e32 v107, v75
	v_permlane16_swap_b32_e32 v124, v92
	v_permlane16_swap_b32_e32 v108, v76
	v_permlane16_swap_b32_e32 v125, v93
	v_permlane16_swap_b32_e32 v109, v77
	v_mul_f32_e32 v181, 0xbfb8aa3b, v122
	v_mul_f32_e32 v193, 0xbfb8aa3b, v106
	v_mul_f32_e32 v195, 0xbfb8aa3b, v123
	v_mul_f32_e32 v199, 0xbfb8aa3b, v107
	v_mul_f32_e32 v201, 0xbfb8aa3b, v124
	v_mul_f32_e32 v202, 0xbfb8aa3b, v108
	v_mul_f32_e32 v203, 0xbfb8aa3b, v125
	v_mul_f32_e32 v206, 0xbfb8aa3b, v109
	v_exp_f32_e32 v181, v181
	v_exp_f32_e32 v193, v193
	v_exp_f32_e32 v195, v195
	v_exp_f32_e32 v199, v199
	v_exp_f32_e32 v201, v201
	v_exp_f32_e32 v202, v202
	v_exp_f32_e32 v203, v203
	v_exp_f32_e32 v206, v206
	v_add_f32_e32 v181, 1.0, v181
	v_add_f32_e32 v193, 1.0, v193
	v_add_f32_e32 v195, 1.0, v195
	v_add_f32_e32 v199, 1.0, v199
	v_add_f32_e32 v201, 1.0, v201
	v_add_f32_e32 v202, 1.0, v202
	v_add_f32_e32 v203, 1.0, v203
	v_add_f32_e32 v206, 1.0, v206
	v_rcp_f32_e32 v181, v181
	v_rcp_f32_e32 v193, v193
	v_rcp_f32_e32 v195, v195
	v_rcp_f32_e32 v199, v199
	v_rcp_f32_e32 v201, v201
	v_rcp_f32_e32 v202, v202
	v_rcp_f32_e32 v203, v203
	v_rcp_f32_e32 v206, v206
	v_mul_f32_e32 v122, v122, v181
	v_mul_f32_e32 v106, v106, v193
	v_mul_f32_e32 v123, v123, v195
	v_mul_f32_e32 v107, v107, v199
	v_mul_f32_e32 v124, v124, v201
	v_mul_f32_e32 v108, v108, v202
	v_mul_f32_e32 v125, v125, v203
	v_mul_f32_e32 v109, v109, v206
	v_mul_f32_e32 v90, v90, v122
	v_mul_f32_e32 v74, v74, v106
	v_mul_f32_e32 v91, v91, v123
	v_mul_f32_e32 v75, v75, v107
	v_mul_f32_e32 v92, v92, v124
	v_mul_f32_e32 v76, v76, v108
	v_mul_f32_e32 v93, v93, v125
	v_mul_f32_e32 v77, v77, v109
	v_cvt_pk_bf16_f32 v122, v90, v74
	v_cvt_pk_bf16_f32 v123, v91, v75
	v_cvt_pk_bf16_f32 v124, v92, v76
	v_cvt_pk_bf16_f32 v125, v93, v77
	global_store_dword v204, v122, s[10:11]
	global_store_dword v204, v123, s[10:11] offset:2048
	global_store_dword v205, v124, s[10:11]
	global_store_dword v205, v125, s[10:11] offset:2048
	s_add_u32 s10, s10, 0x4000
	s_addc_u32 s11, s11, 0
	v_permlane16_swap_b32_e32 v126, v94
	v_permlane16_swap_b32_e32 v110, v78
	v_permlane16_swap_b32_e32 v127, v95
	v_permlane16_swap_b32_e32 v111, v79
	v_permlane16_swap_b32_e32 v128, v96
	v_permlane16_swap_b32_e32 v112, v80
	v_permlane16_swap_b32_e32 v129, v97
	v_permlane16_swap_b32_e32 v113, v81
	v_mul_f32_e32 v181, 0xbfb8aa3b, v126
	v_mul_f32_e32 v193, 0xbfb8aa3b, v110
	v_mul_f32_e32 v195, 0xbfb8aa3b, v127
	v_mul_f32_e32 v199, 0xbfb8aa3b, v111
	v_mul_f32_e32 v201, 0xbfb8aa3b, v128
	v_mul_f32_e32 v202, 0xbfb8aa3b, v112
	v_mul_f32_e32 v203, 0xbfb8aa3b, v129
	v_mul_f32_e32 v206, 0xbfb8aa3b, v113
	v_exp_f32_e32 v181, v181
	v_exp_f32_e32 v193, v193
	v_exp_f32_e32 v195, v195
	v_exp_f32_e32 v199, v199
	v_exp_f32_e32 v201, v201
	v_exp_f32_e32 v202, v202
	v_exp_f32_e32 v203, v203
	v_exp_f32_e32 v206, v206
	v_add_f32_e32 v181, 1.0, v181
	v_add_f32_e32 v193, 1.0, v193
	v_add_f32_e32 v195, 1.0, v195
	v_add_f32_e32 v199, 1.0, v199
	v_add_f32_e32 v201, 1.0, v201
	v_add_f32_e32 v202, 1.0, v202
	v_add_f32_e32 v203, 1.0, v203
	v_add_f32_e32 v206, 1.0, v206
	v_rcp_f32_e32 v181, v181
	v_rcp_f32_e32 v193, v193
	v_rcp_f32_e32 v195, v195
	v_rcp_f32_e32 v199, v199
	v_rcp_f32_e32 v201, v201
	v_rcp_f32_e32 v202, v202
	v_rcp_f32_e32 v203, v203
	v_rcp_f32_e32 v206, v206
	v_mul_f32_e32 v126, v126, v181
	v_mul_f32_e32 v110, v110, v193
	v_mul_f32_e32 v127, v127, v195
	v_mul_f32_e32 v111, v111, v199
	v_mul_f32_e32 v128, v128, v201
	v_mul_f32_e32 v112, v112, v202
	v_mul_f32_e32 v129, v129, v203
	v_mul_f32_e32 v113, v113, v206
	v_mul_f32_e32 v94, v94, v126
	v_mul_f32_e32 v78, v78, v110
	v_mul_f32_e32 v95, v95, v127
	v_mul_f32_e32 v79, v79, v111
	v_mul_f32_e32 v96, v96, v128
	v_mul_f32_e32 v80, v80, v112
	v_mul_f32_e32 v97, v97, v129
	v_mul_f32_e32 v81, v81, v113
	v_cvt_pk_bf16_f32 v126, v94, v78
	v_cvt_pk_bf16_f32 v127, v95, v79
	v_cvt_pk_bf16_f32 v128, v96, v80
	v_cvt_pk_bf16_f32 v129, v97, v81
	global_store_dword v204, v126, s[10:11]
	global_store_dword v204, v127, s[10:11] offset:2048
	global_store_dword v205, v128, s[10:11]
	global_store_dword v205, v129, s[10:11] offset:2048
	s_add_u32 s10, s10, 0x4000
	s_addc_u32 s11, s11, 0
	v_permlane16_swap_b32_e32 v50, v18
	v_permlane16_swap_b32_e32 v34, v2
	v_permlane16_swap_b32_e32 v51, v19
	v_permlane16_swap_b32_e32 v35, v3
	v_permlane16_swap_b32_e32 v52, v20
	v_permlane16_swap_b32_e32 v36, v4
	v_permlane16_swap_b32_e32 v53, v21
	v_permlane16_swap_b32_e32 v37, v5
	v_mul_f32_e32 v181, 0xbfb8aa3b, v50
	v_mul_f32_e32 v193, 0xbfb8aa3b, v34
	v_mul_f32_e32 v195, 0xbfb8aa3b, v51
	v_mul_f32_e32 v199, 0xbfb8aa3b, v35
	v_mul_f32_e32 v201, 0xbfb8aa3b, v52
	v_mul_f32_e32 v202, 0xbfb8aa3b, v36
	v_mul_f32_e32 v203, 0xbfb8aa3b, v53
	v_mul_f32_e32 v206, 0xbfb8aa3b, v37
	v_exp_f32_e32 v181, v181
	v_exp_f32_e32 v193, v193
	v_exp_f32_e32 v195, v195
	v_exp_f32_e32 v199, v199
	v_exp_f32_e32 v201, v201
	v_exp_f32_e32 v202, v202
	v_exp_f32_e32 v203, v203
	v_exp_f32_e32 v206, v206
	v_add_f32_e32 v181, 1.0, v181
	v_add_f32_e32 v193, 1.0, v193
	v_add_f32_e32 v195, 1.0, v195
	v_add_f32_e32 v199, 1.0, v199
	v_add_f32_e32 v201, 1.0, v201
	v_add_f32_e32 v202, 1.0, v202
	v_add_f32_e32 v203, 1.0, v203
	v_add_f32_e32 v206, 1.0, v206
	v_rcp_f32_e32 v181, v181
	v_rcp_f32_e32 v193, v193
	v_rcp_f32_e32 v195, v195
	v_rcp_f32_e32 v199, v199
	v_rcp_f32_e32 v201, v201
	v_rcp_f32_e32 v202, v202
	v_rcp_f32_e32 v203, v203
	v_rcp_f32_e32 v206, v206
	v_mul_f32_e32 v50, v50, v181
	v_mul_f32_e32 v34, v34, v193
	v_mul_f32_e32 v51, v51, v195
	v_mul_f32_e32 v35, v35, v199
	v_mul_f32_e32 v52, v52, v201
	v_mul_f32_e32 v36, v36, v202
	v_mul_f32_e32 v53, v53, v203
	v_mul_f32_e32 v37, v37, v206
	v_mul_f32_e32 v18, v18, v50
	v_mul_f32_e32 v2, v2, v34
	v_mul_f32_e32 v19, v19, v51
	v_mul_f32_e32 v3, v3, v35
	v_mul_f32_e32 v20, v20, v52
	v_mul_f32_e32 v4, v4, v36
	v_mul_f32_e32 v21, v21, v53
	v_mul_f32_e32 v5, v5, v37
	v_cvt_pk_bf16_f32 v50, v18, v2
	v_cvt_pk_bf16_f32 v51, v19, v3
	v_cvt_pk_bf16_f32 v52, v20, v4
	v_cvt_pk_bf16_f32 v53, v21, v5
	global_store_dword v204, v50, s[10:11]
	global_store_dword v204, v51, s[10:11] offset:2048
	global_store_dword v205, v52, s[10:11]
	global_store_dword v205, v53, s[10:11] offset:2048
	s_add_u32 s10, s10, 0x4000
	s_addc_u32 s11, s11, 0
	v_permlane16_swap_b32_e32 v54, v22
	v_permlane16_swap_b32_e32 v38, v6
	v_permlane16_swap_b32_e32 v55, v23
	v_permlane16_swap_b32_e32 v39, v7
	v_permlane16_swap_b32_e32 v56, v24
	v_permlane16_swap_b32_e32 v40, v8
	v_permlane16_swap_b32_e32 v57, v25
	v_permlane16_swap_b32_e32 v41, v9
	v_mul_f32_e32 v181, 0xbfb8aa3b, v54
	v_mul_f32_e32 v193, 0xbfb8aa3b, v38
	v_mul_f32_e32 v195, 0xbfb8aa3b, v55
	v_mul_f32_e32 v199, 0xbfb8aa3b, v39
	v_mul_f32_e32 v201, 0xbfb8aa3b, v56
	v_mul_f32_e32 v202, 0xbfb8aa3b, v40
	v_mul_f32_e32 v203, 0xbfb8aa3b, v57
	v_mul_f32_e32 v206, 0xbfb8aa3b, v41
	v_exp_f32_e32 v181, v181
	v_exp_f32_e32 v193, v193
	v_exp_f32_e32 v195, v195
	v_exp_f32_e32 v199, v199
	v_exp_f32_e32 v201, v201
	v_exp_f32_e32 v202, v202
	v_exp_f32_e32 v203, v203
	v_exp_f32_e32 v206, v206
	v_add_f32_e32 v181, 1.0, v181
	v_add_f32_e32 v193, 1.0, v193
	v_add_f32_e32 v195, 1.0, v195
	v_add_f32_e32 v199, 1.0, v199
	v_add_f32_e32 v201, 1.0, v201
	v_add_f32_e32 v202, 1.0, v202
	v_add_f32_e32 v203, 1.0, v203
	v_add_f32_e32 v206, 1.0, v206
	v_rcp_f32_e32 v181, v181
	v_rcp_f32_e32 v193, v193
	v_rcp_f32_e32 v195, v195
	v_rcp_f32_e32 v199, v199
	v_rcp_f32_e32 v201, v201
	v_rcp_f32_e32 v202, v202
	v_rcp_f32_e32 v203, v203
	v_rcp_f32_e32 v206, v206
	v_mul_f32_e32 v54, v54, v181
	v_mul_f32_e32 v38, v38, v193
	v_mul_f32_e32 v55, v55, v195
	v_mul_f32_e32 v39, v39, v199
	v_mul_f32_e32 v56, v56, v201
	v_mul_f32_e32 v40, v40, v202
	v_mul_f32_e32 v57, v57, v203
	v_mul_f32_e32 v41, v41, v206
	v_mul_f32_e32 v22, v22, v54
	v_mul_f32_e32 v6, v6, v38
	v_mul_f32_e32 v23, v23, v55
	v_mul_f32_e32 v7, v7, v39
	v_mul_f32_e32 v24, v24, v56
	v_mul_f32_e32 v8, v8, v40
	v_mul_f32_e32 v25, v25, v57
	v_mul_f32_e32 v9, v9, v41
	v_cvt_pk_bf16_f32 v54, v22, v6
	v_cvt_pk_bf16_f32 v55, v23, v7
	v_cvt_pk_bf16_f32 v56, v24, v8
	v_cvt_pk_bf16_f32 v57, v25, v9
	global_store_dword v204, v54, s[10:11]
	global_store_dword v204, v55, s[10:11] offset:2048
	global_store_dword v205, v56, s[10:11]
	global_store_dword v205, v57, s[10:11] offset:2048
	s_add_u32 s10, s10, 0x4000
	s_addc_u32 s11, s11, 0
	v_permlane16_swap_b32_e32 v58, v26
	v_permlane16_swap_b32_e32 v42, v10
	v_permlane16_swap_b32_e32 v59, v27
	v_permlane16_swap_b32_e32 v43, v11
	v_permlane16_swap_b32_e32 v60, v28
	v_permlane16_swap_b32_e32 v44, v12
	v_permlane16_swap_b32_e32 v61, v29
	v_permlane16_swap_b32_e32 v45, v13
	v_mul_f32_e32 v181, 0xbfb8aa3b, v58
	v_mul_f32_e32 v193, 0xbfb8aa3b, v42
	v_mul_f32_e32 v195, 0xbfb8aa3b, v59
	v_mul_f32_e32 v199, 0xbfb8aa3b, v43
	v_mul_f32_e32 v201, 0xbfb8aa3b, v60
	v_mul_f32_e32 v202, 0xbfb8aa3b, v44
	v_mul_f32_e32 v203, 0xbfb8aa3b, v61
	v_mul_f32_e32 v206, 0xbfb8aa3b, v45
	v_exp_f32_e32 v181, v181
	v_exp_f32_e32 v193, v193
	v_exp_f32_e32 v195, v195
	v_exp_f32_e32 v199, v199
	v_exp_f32_e32 v201, v201
	v_exp_f32_e32 v202, v202
	v_exp_f32_e32 v203, v203
	v_exp_f32_e32 v206, v206
	v_add_f32_e32 v181, 1.0, v181
	v_add_f32_e32 v193, 1.0, v193
	v_add_f32_e32 v195, 1.0, v195
	v_add_f32_e32 v199, 1.0, v199
	v_add_f32_e32 v201, 1.0, v201
	v_add_f32_e32 v202, 1.0, v202
	v_add_f32_e32 v203, 1.0, v203
	v_add_f32_e32 v206, 1.0, v206
	v_rcp_f32_e32 v181, v181
	v_rcp_f32_e32 v193, v193
	v_rcp_f32_e32 v195, v195
	v_rcp_f32_e32 v199, v199
	v_rcp_f32_e32 v201, v201
	v_rcp_f32_e32 v202, v202
	v_rcp_f32_e32 v203, v203
	v_rcp_f32_e32 v206, v206
	v_mul_f32_e32 v58, v58, v181
	v_mul_f32_e32 v42, v42, v193
	v_mul_f32_e32 v59, v59, v195
	v_mul_f32_e32 v43, v43, v199
	v_mul_f32_e32 v60, v60, v201
	v_mul_f32_e32 v44, v44, v202
	v_mul_f32_e32 v61, v61, v203
	v_mul_f32_e32 v45, v45, v206
	v_mul_f32_e32 v26, v26, v58
	v_mul_f32_e32 v10, v10, v42
	v_mul_f32_e32 v27, v27, v59
	v_mul_f32_e32 v11, v11, v43
	v_mul_f32_e32 v28, v28, v60
	v_mul_f32_e32 v12, v12, v44
	v_mul_f32_e32 v29, v29, v61
	v_mul_f32_e32 v13, v13, v45
	v_cvt_pk_bf16_f32 v58, v26, v10
	v_cvt_pk_bf16_f32 v59, v27, v11
	v_cvt_pk_bf16_f32 v60, v28, v12
	v_cvt_pk_bf16_f32 v61, v29, v13
	global_store_dword v204, v58, s[10:11]
	global_store_dword v204, v59, s[10:11] offset:2048
	global_store_dword v205, v60, s[10:11]
	global_store_dword v205, v61, s[10:11] offset:2048
	s_add_u32 s10, s10, 0x4000
	s_addc_u32 s11, s11, 0
	v_permlane16_swap_b32_e32 v62, v30
	v_permlane16_swap_b32_e32 v46, v14
	v_permlane16_swap_b32_e32 v63, v31
	v_permlane16_swap_b32_e32 v47, v15
	v_permlane16_swap_b32_e32 v64, v32
	v_permlane16_swap_b32_e32 v48, v16
	v_permlane16_swap_b32_e32 v65, v33
	v_permlane16_swap_b32_e32 v49, v17
	v_mul_f32_e32 v181, 0xbfb8aa3b, v62
	v_mul_f32_e32 v193, 0xbfb8aa3b, v46
	v_mul_f32_e32 v195, 0xbfb8aa3b, v63
	v_mul_f32_e32 v199, 0xbfb8aa3b, v47
	v_mul_f32_e32 v201, 0xbfb8aa3b, v64
	v_mul_f32_e32 v202, 0xbfb8aa3b, v48
	v_mul_f32_e32 v203, 0xbfb8aa3b, v65
	v_mul_f32_e32 v206, 0xbfb8aa3b, v49
	v_exp_f32_e32 v181, v181
	v_exp_f32_e32 v193, v193
	v_exp_f32_e32 v195, v195
	v_exp_f32_e32 v199, v199
	v_exp_f32_e32 v201, v201
	v_exp_f32_e32 v202, v202
	v_exp_f32_e32 v203, v203
	v_exp_f32_e32 v206, v206
	v_add_f32_e32 v181, 1.0, v181
	v_add_f32_e32 v193, 1.0, v193
	v_add_f32_e32 v195, 1.0, v195
	v_add_f32_e32 v199, 1.0, v199
	v_add_f32_e32 v201, 1.0, v201
	v_add_f32_e32 v202, 1.0, v202
	v_add_f32_e32 v203, 1.0, v203
	v_add_f32_e32 v206, 1.0, v206
	v_rcp_f32_e32 v181, v181
	v_rcp_f32_e32 v193, v193
	v_rcp_f32_e32 v195, v195
	v_rcp_f32_e32 v199, v199
	v_rcp_f32_e32 v201, v201
	v_rcp_f32_e32 v202, v202
	v_rcp_f32_e32 v203, v203
	v_rcp_f32_e32 v206, v206
	v_mul_f32_e32 v62, v62, v181
	v_mul_f32_e32 v46, v46, v193
	v_mul_f32_e32 v63, v63, v195
	v_mul_f32_e32 v47, v47, v199
	v_mul_f32_e32 v64, v64, v201
	v_mul_f32_e32 v48, v48, v202
	v_mul_f32_e32 v65, v65, v203
	v_mul_f32_e32 v49, v49, v206
	v_mul_f32_e32 v30, v30, v62
	v_mul_f32_e32 v14, v14, v46
	v_mul_f32_e32 v31, v31, v63
	v_mul_f32_e32 v15, v15, v47
	v_mul_f32_e32 v32, v32, v64
	v_mul_f32_e32 v16, v16, v48
	v_mul_f32_e32 v33, v33, v65
	v_mul_f32_e32 v17, v17, v49
	v_cvt_pk_bf16_f32 v62, v30, v14
	v_cvt_pk_bf16_f32 v63, v31, v15
	v_cvt_pk_bf16_f32 v64, v32, v16
	v_cvt_pk_bf16_f32 v65, v33, v17
	global_store_dword v204, v62, s[10:11]
	global_store_dword v204, v63, s[10:11] offset:2048
	global_store_dword v205, v64, s[10:11]
	global_store_dword v205, v65, s[10:11] offset:2048
	s_and_b64 vcc, exec, s[8:9]
	s_mov_b32 s37, s36
	s_cbranch_vccnz .LBB0_1365
.LBB0_1358:
	s_add_i32 s36, s37, s86
	s_cmp_ge_i32 s36, s12
	s_cselect_b64 s[8:9], -1, 0
	s_and_b64 vcc, exec, s[8:9]
	s_mov_b64 s[10:11], s[6:7]
	v_mov_b32_e32 v170, 0
	v_mov_b32_e32 v171, 0
	v_mov_b32_e32 v172, 0
	v_mov_b32_e32 v173, 0
	v_mov_b32_e32 v174, 0
	v_mov_b32_e32 v175, 0
	v_mov_b32_e32 v176, 0
	v_mov_b32_e32 v177, 0
	s_mov_b32 s38, s35
	s_cbranch_vccnz .LBB0_1360
	s_mul_hi_u32 s40, s36, 0xaaaaaaab
	s_lshr_b32 s0, s40, 6
	v_readlane_b32 s10, v245, 12
	s_add_i32 s10, s0, s10
	s_mulk_i32 s0, 0x60
	s_sub_i32 s0, s36, s0
	s_mul_i32 s11, s0, 0xab
	s_bfe_u32 s41, s11, 0x6000a
	s_mul_i32 s11, s41, 6
	s_sub_i32 s11, s0, s11
	s_mul_i32 s0, s10, 0x600
	s_lshl_b64 s[38:39], s[0:1], 2
	s_add_u32 s0, s16, s38
	s_addc_u32 s39, s17, s39
	s_and_b32 s11, s11, 0xff
	s_lshl_b32 s11, s11, 10
	s_add_u32 s38, s0, s11
	s_addc_u32 s39, s39, 0
	v_lshl_add_u64 v[2:3], v[178:179], 2, s[38:39]
	global_load_dword v170, v[2:3], off
	global_load_dword v171, v[2:3], off offset:32
	global_load_dword v172, v[2:3], off offset:64
	global_load_dword v173, v[2:3], off offset:96
	global_load_dword v174, v[2:3], off offset:128
	global_load_dword v175, v[2:3], off offset:160
	global_load_dword v176, v[2:3], off offset:192
	global_load_dword v177, v[2:3], off offset:224
	s_mov_b32 s11, s1
	s_lshl_b64 s[10:11], s[10:11], 23
	s_add_u32 s0, s13, s10
	s_addc_u32 s11, s34, s11
	s_lshl_b32 s10, s41, 8
	s_add_u32 s10, s0, s10
	s_addc_u32 s11, s11, 0
	s_lshr_b32 s0, s40, 2
	s_mul_i32 s0, s0, 6
	s_bfe_u32 s38, s40, 0x10002
	s_sub_i32 s0, s36, s0
	s_add_i32 s38, s38, s0
	s_nop 0

.Lg6_switch:
	v_lshl_add_u32 v162, v170, 11, v196
	v_lshl_add_u32 v163, v171, 11, v215
	v_lshl_add_u32 v164, v172, 11, v196
	v_lshl_add_u32 v165, v173, 11, v215
	v_lshl_add_u32 v166, v174, 11, v196
	v_lshl_add_u32 v167, v175, 11, v215
	v_lshl_add_u32 v168, v176, 11, v196
	v_lshl_add_u32 v169, v177, 11, v215
	v_add_u32_e32 v162, 0x1000, v162
	v_add_u32_e32 v163, 0xc00, v163
	v_add_u32_e32 v164, 0x800, v164
	v_add_u32_e32 v165, 0x400, v165
	v_add_u32_e32 v166, 0x1000, v166
	v_add_u32_e32 v167, 0xc00, v167
	v_add_u32_e32 v168, 0x800, v168
	v_add_u32_e32 v169, 0x400, v169
	s_mov_b64 s[6:7], s[10:11]
	s_mov_b32 s35, s38
	s_mov_b32 s52, -2
	s_branch .Lg6_noswitch

.LBB0_1418:
	s_mul_hi_u32 s0, s38, 0xaaaaaaab
	s_lshr_b32 s0, s0, 5
	v_readlane_b32 s8, v245, 12
	s_add_i32 s41, s0, s8
	s_mul_i32 s0, s0, 48
	s_sub_i32 s0, s38, s0
	s_mul_i32 s8, s0, 0xab
	s_bfe_u32 s40, s8, 0x6000a
	s_mul_i32 s8, s40, 6
	s_sub_i32 s0, s0, s8
	s_and_b32 s0, s0, 0xff
	s_mul_i32 s42, s41, 0x600
	s_lshl_b32 s43, s0, 8
	s_add_i32 s0, s43, s42
	v_add_u32_e32 v2, s0, v198
	v_readlane_b32 s44, v247, 49
	v_ashrrev_i32_e32 v3, 31, v2
	v_readlane_b32 s58, v247, 63
	v_readlane_b32 s59, v246, 0
	s_xor_b32 s37, s37, 1
	s_add_i32 s38, s38, s86
	v_lshl_add_u64 v[2:3], v[2:3], 2, s[58:59]
	global_load_dword v202, v[2:3], off
	s_cmp_ge_i32 s38, s34
	s_cselect_b64 s[8:9], -1, 0
	v_lshl_add_u32 v3, s37, 10, v204
	s_and_b64 vcc, exec, s[8:9]
	s_mov_b64 s[10:11], s[6:7]
	s_mov_b64 s[12:13], s[4:5]
	s_mov_b32 s44, s39
	v_readlane_b32 s45, v247, 50
	v_readlane_b32 s46, v247, 51
	v_readlane_b32 s47, v247, 52
	v_readlane_b32 s48, v247, 53
	v_readlane_b32 s49, v247, 54
	v_readlane_b32 s50, v247, 55
	v_readlane_b32 s51, v247, 56
	v_readlane_b32 s52, v247, 57
	v_readlane_b32 s53, v247, 58
	v_readlane_b32 s54, v247, 59
	v_readlane_b32 s55, v247, 60
	v_readlane_b32 s56, v247, 61
	v_readlane_b32 s57, v247, 62
	s_nop 0
	s_nop 0
	s_cbranch_vccnz .LBB0_1420
	s_mul_hi_u32 s44, s38, 0xaaaaaaab
	s_lshr_b32 s10, s44, 5
	v_readlane_b32 s0, v245, 12
	s_add_i32 s0, s10, s0
	s_mul_i32 s10, s10, 48
	s_sub_i32 s10, s38, s10
	s_mul_i32 s11, s10, 0xab
	s_bfe_u32 s45, s11, 0x6000a
	s_mul_i32 s11, s45, 6
	s_sub_i32 s10, s10, s11
	s_and_b32 s10, s10, 0xff
	s_lshl_b32 s10, s10, 19
	s_add_u32 s10, s24, s10
	s_mul_i32 s12, s0, 0x300000
	s_addc_u32 s13, s25, 0
	s_mul_hi_u32 s11, s0, 0x300000
	s_add_u32 s10, s10, s12
	s_addc_u32 s11, s13, s11
	s_lshl_b64 s[12:13], s[0:1], 22
	s_add_u32 s0, s35, s12
	s_addc_u32 s13, s36, s13
	s_lshl_b32 s12, s45, 9
	s_add_u32 s12, s0, s12
	s_addc_u32 s13, s13, 0
	s_lshr_b32 s0, s44, 2
	s_mul_i32 s0, s0, 6
	s_sub_i32 s0, s38, s0
	s_bfe_u32 s44, s44, 0x10002
	s_add_i32 s44, s44, s0
